# dt fold with four per-wave-column K-loop copies (no wave-column branching inside the MFMA blocks)
# baseline (speedup 1.0000x reference)
.LBB0_397:
	v_readlane_b32 s56, v244, 0
	v_readlane_b32 s57, v244, 1
	v_readlane_b32 s58, v244, 2
	v_readlane_b32 s59, v244, 3
	v_readlane_b32 s60, v244, 4
	v_readlane_b32 s61, v244, 5
	s_ashr_i32 s25, s24, 31
	v_readlane_b32 s62, v244, 6
	v_readlane_b32 s63, v244, 7
	s_mov_b64 s[56:57], s[60:61]
	s_lshl_b64 s[26:27], s[24:25], 19
	s_mov_b64 s[58:59], s[62:63]
	s_add_u32 s26, s58, s26
	s_addc_u32 s27, s59, s27
	s_and_b64 s[28:29], s[0:1], exec
	s_cselect_b32 s5, s27, s31
	s_cselect_b32 s8, s26, s30
	s_ashr_i32 s19, s18, 31
	s_lshl_b64 s[28:29], s[18:19], 19
	s_add_u32 s28, s33, s28
	s_addc_u32 s29, s38, s29
	s_and_b64 s[36:37], s[0:1], exec
	s_cselect_b32 s19, s29, s35
	s_cselect_b32 s25, s28, s34
	s_add_u32 s30, s30, 0x40080
	s_addc_u32 s31, s31, 0
	s_add_u32 s53, s34, 0x100
	v_mov_b32_e32 v0, 0
	s_addc_u32 s54, s35, 0
	s_mov_b32 s55, -2
	v_mov_b32_e32 v1, v0
	v_mov_b32_e32 v2, v0
	v_mov_b32_e32 v3, v0
	v_mov_b32_e32 v4, v0
	v_mov_b32_e32 v5, v0
	v_mov_b32_e32 v6, v0
	v_mov_b32_e32 v7, v0
	v_mov_b32_e32 v16, v0
	v_mov_b32_e32 v17, v0
	v_mov_b32_e32 v18, v0
	v_mov_b32_e32 v19, v0
	v_mov_b32_e32 v20, v0
	v_mov_b32_e32 v21, v0
	v_mov_b32_e32 v22, v0
	v_mov_b32_e32 v23, v0
	v_mov_b32_e32 v32, v0
	v_mov_b32_e32 v33, v0
	v_mov_b32_e32 v34, v0
	v_mov_b32_e32 v35, v0
	v_mov_b32_e32 v36, v0
	v_mov_b32_e32 v37, v0
	v_mov_b32_e32 v38, v0
	v_mov_b32_e32 v39, v0
	v_mov_b32_e32 v48, v0
	v_mov_b32_e32 v49, v0
	v_mov_b32_e32 v50, v0
	v_mov_b32_e32 v51, v0
	v_mov_b32_e32 v52, v0
	v_mov_b32_e32 v53, v0
	v_mov_b32_e32 v54, v0
	v_mov_b32_e32 v55, v0
	v_mov_b32_e32 v8, v0
	v_mov_b32_e32 v9, v0
	v_mov_b32_e32 v10, v0
	v_mov_b32_e32 v11, v0
	v_mov_b32_e32 v12, v0
	v_mov_b32_e32 v13, v0
	v_mov_b32_e32 v14, v0
	v_mov_b32_e32 v15, v0
	v_mov_b32_e32 v24, v0
	v_mov_b32_e32 v25, v0
	v_mov_b32_e32 v26, v0
	v_mov_b32_e32 v27, v0
	v_mov_b32_e32 v28, v0
	v_mov_b32_e32 v29, v0
	v_mov_b32_e32 v30, v0
	v_mov_b32_e32 v31, v0
	v_mov_b32_e32 v40, v0
	v_mov_b32_e32 v41, v0
	v_mov_b32_e32 v42, v0
	v_mov_b32_e32 v43, v0
	v_mov_b32_e32 v44, v0
	v_mov_b32_e32 v45, v0
	v_mov_b32_e32 v46, v0
	v_mov_b32_e32 v47, v0
	v_mov_b32_e32 v56, v0
	v_mov_b32_e32 v57, v0
	v_mov_b32_e32 v58, v0
	v_mov_b32_e32 v59, v0
	v_mov_b32_e32 v60, v0
	v_mov_b32_e32 v61, v0
	v_mov_b32_e32 v62, v0
	v_mov_b32_e32 v63, v0
	v_mov_b32_e32 v64, v0
	v_mov_b32_e32 v65, v0
	v_mov_b32_e32 v66, v0
	v_mov_b32_e32 v67, v0
	v_mov_b32_e32 v68, v0
	v_mov_b32_e32 v69, v0
	v_mov_b32_e32 v70, v0
	v_mov_b32_e32 v71, v0
	v_mov_b32_e32 v80, v0
	v_mov_b32_e32 v81, v0
	v_mov_b32_e32 v82, v0
	v_mov_b32_e32 v83, v0
	v_mov_b32_e32 v84, v0
	v_mov_b32_e32 v85, v0
	v_mov_b32_e32 v86, v0
	v_mov_b32_e32 v87, v0
	v_mov_b32_e32 v96, v0
	v_mov_b32_e32 v97, v0
	v_mov_b32_e32 v98, v0
	v_mov_b32_e32 v99, v0
	v_mov_b32_e32 v100, v0
	v_mov_b32_e32 v101, v0
	v_mov_b32_e32 v102, v0
	v_mov_b32_e32 v103, v0
	v_mov_b32_e32 v112, v0
	v_mov_b32_e32 v113, v0
	v_mov_b32_e32 v114, v0
	v_mov_b32_e32 v115, v0
	v_mov_b32_e32 v116, v0
	v_mov_b32_e32 v117, v0
	v_mov_b32_e32 v118, v0
	v_mov_b32_e32 v119, v0
	v_mov_b32_e32 v72, v0
	v_mov_b32_e32 v73, v0
	v_mov_b32_e32 v74, v0
	v_mov_b32_e32 v75, v0
	v_mov_b32_e32 v76, v0
	v_mov_b32_e32 v77, v0
	v_mov_b32_e32 v78, v0
	v_mov_b32_e32 v79, v0
	v_mov_b32_e32 v88, v0
	v_mov_b32_e32 v89, v0
	v_mov_b32_e32 v90, v0
	v_mov_b32_e32 v91, v0
	v_mov_b32_e32 v92, v0
	v_mov_b32_e32 v93, v0
	v_mov_b32_e32 v94, v0
	v_mov_b32_e32 v95, v0
	v_mov_b32_e32 v104, v0
	v_mov_b32_e32 v105, v0
	v_mov_b32_e32 v106, v0
	v_mov_b32_e32 v107, v0
	v_mov_b32_e32 v108, v0
	v_mov_b32_e32 v109, v0
	v_mov_b32_e32 v110, v0
	v_mov_b32_e32 v111, v0
	v_mov_b32_e32 v120, v0
	v_mov_b32_e32 v121, v0
	v_mov_b32_e32 v122, v0
	v_mov_b32_e32 v123, v0
	v_mov_b32_e32 v124, v0
	v_mov_b32_e32 v125, v0
	v_mov_b32_e32 v126, v0
	v_mov_b32_e32 v127, v0
	s_cmp_eq_u32 s6, 0
	s_cselect_b32 s84, 1, 0
	s_cbranch_scc0 .Ldtf_nosetup
	v_readfirstlane_b32 s85, v182
	s_bfe_u32 s85, s85, 0x20006
	v_readlane_b32 s98, v244, 6
	v_readlane_b32 s99, v244, 7
	s_add_u32 s100, s98, 0x1a000000
	s_addc_u32 s101, s99, 0
	s_add_u32 s98, s98, 0x18600000
	s_addc_u32 s99, s99, 0
	v_and_b32_e32 v245, 15, v182
	v_bfe_u32 v254, v182, 4, 2
	v_lshlrev_b32_e32 v245, 11, v245
	v_lshl_add_u32 v245, v254, 4, v245
	v_mov_b32_e32 v246, 0
	v_mov_b32_e32 v247, 0
	v_mov_b32_e32 v248, 0
	v_mov_b32_e32 v249, 0
	v_mov_b32_e32 v250, 0
	v_mov_b32_e32 v251, 0
	v_mov_b32_e32 v252, 0
	v_mov_b32_e32 v253, 0
	global_load_dwordx4 v[232:235], v245, s[98:99]
	global_load_dwordx4 v[236:239], v245, s[98:99] offset:64
	s_add_u32 s98, s98, 0x80
	s_addc_u32 s99, s99, 0
	s_waitcnt vmcnt(0)
	s_cmp_lt_u32 s85, 2
	s_cbranch_scc1 .Ldtf_d01
	s_cmp_eq_u32 s85, 2
	s_cbranch_scc1 .Ldtf_loop2
	s_branch .Ldtf_loop3
.Ldtf_d01:
	s_cmp_eq_u32 s85, 0
	s_cbranch_scc1 .Ldtf_loop0
	s_branch .Ldtf_loop1

.Ldtf_loop0:
	ds_read_b128 v[158:161], v154
	ds_read_b128 v[162:165], v154 offset:1024
	ds_read_b128 v[166:169], v154 offset:2048
	ds_read_b128 v[170:173], v154 offset:3072
	ds_read_b128 v[174:177], v155
	ds_read_b128 v[178:181], v155 offset:1024
	ds_read_b128 v[184:187], v155 offset:2048
	ds_read_b128 v[188:191], v155 offset:3072
	s_add_u32 s34, s30, 0xfffc0080
	s_addc_u32 s35, s31, -1
	s_cmp_eq_u32 s55, 12
	s_cselect_b32 s37, s5, s35
	s_cselect_b32 s36, s8, s34
	s_cselect_b32 s35, s19, s54
	s_cselect_b32 s34, s25, s53
	v_lshl_add_u64 v[152:153], s[30:31], 0, v[142:143]
	s_add_i32 m0, s7, 0xc000
	ds_read_b128 v[192:195], v156
	ds_read_b128 v[196:199], v156 offset:1024
	ds_read_b128 v[200:203], v156 offset:2048
	ds_read_b128 v[204:207], v156 offset:3072
	ds_read_b128 v[208:211], v156 offset:4096
	ds_read_b128 v[212:215], v156 offset:5120
	ds_read_b128 v[216:219], v156 offset:6144
	ds_read_b128 v[220:223], v156 offset:7168
	global_load_lds_dwordx4 v[152:153], off
	v_lshl_add_u64 v[152:153], s[30:31], 0, v[146:147]
	s_add_i32 m0, s7, 0xe000
	s_nop 0
	global_load_lds_dwordx4 v[152:153], off
	global_load_dwordx4 v[240:243], v245, s[98:99]
	global_load_dwordx4 v[148:151], v245, s[98:99] offset:64
	s_add_u32 s98, s98, 0x80
	s_addc_u32 s99, s99, 0
	s_waitcnt vmcnt(10)
	s_waitcnt lgkmcnt(0)
	s_barrier
	s_setprio 1
	s_waitcnt lgkmcnt(0)
	v_mfma_f32_16x16x32_bf16 v[124:127], v[158:161], v[192:195], v[124:127]
	v_mfma_f32_16x16x32_bf16 v[120:123], v[166:169], v[192:195], v[120:123]
	v_mfma_f32_16x16x32_bf16 v[108:111], v[158:161], v[200:203], v[108:111]
	v_mfma_f32_16x16x32_bf16 v[104:107], v[166:169], v[200:203], v[104:107]
	v_mfma_f32_16x16x32_bf16 v[92:95], v[158:161], v[208:211], v[92:95]
	v_mfma_f32_16x16x32_bf16 v[88:91], v[166:169], v[208:211], v[88:91]
	v_mfma_f32_16x16x32_bf16 v[76:79], v[158:161], v[216:219], v[76:79]
	v_mfma_f32_16x16x32_bf16 v[72:75], v[166:169], v[216:219], v[72:75]
	v_mfma_f32_16x16x32_bf16 v[124:127], v[162:165], v[196:199], v[124:127]
	v_mfma_f32_16x16x32_bf16 v[120:123], v[170:173], v[196:199], v[120:123]
	v_mfma_f32_16x16x32_bf16 v[108:111], v[162:165], v[204:207], v[108:111]
	v_mfma_f32_16x16x32_bf16 v[104:107], v[170:173], v[204:207], v[104:107]
	v_mfma_f32_16x16x32_bf16 v[92:95], v[162:165], v[212:215], v[92:95]
	v_mfma_f32_16x16x32_bf16 v[88:91], v[170:173], v[212:215], v[88:91]
	v_mfma_f32_16x16x32_bf16 v[76:79], v[162:165], v[220:223], v[76:79]
	v_mfma_f32_16x16x32_bf16 v[72:75], v[170:173], v[220:223], v[72:75]
	s_setprio 0
	s_setprio 1
	v_mfma_f32_16x16x32_bf16 v[116:119], v[174:177], v[192:195], v[116:119]
	v_mfma_f32_16x16x32_bf16 v[112:115], v[184:187], v[192:195], v[112:115]
	v_mfma_f32_16x16x32_bf16 v[100:103], v[174:177], v[200:203], v[100:103]
	v_mfma_f32_16x16x32_bf16 v[96:99], v[184:187], v[200:203], v[96:99]
	v_mfma_f32_16x16x32_bf16 v[84:87], v[174:177], v[208:211], v[84:87]
	v_mfma_f32_16x16x32_bf16 v[80:83], v[184:187], v[208:211], v[80:83]
	v_mfma_f32_16x16x32_bf16 v[68:71], v[174:177], v[216:219], v[68:71]
	v_mfma_f32_16x16x32_bf16 v[64:67], v[184:187], v[216:219], v[64:67]
	v_mfma_f32_16x16x32_bf16 v[116:119], v[178:181], v[196:199], v[116:119]
	v_mfma_f32_16x16x32_bf16 v[112:115], v[188:191], v[196:199], v[112:115]
	v_mfma_f32_16x16x32_bf16 v[100:103], v[178:181], v[204:207], v[100:103]
	v_mfma_f32_16x16x32_bf16 v[96:99], v[188:191], v[204:207], v[96:99]
	v_mfma_f32_16x16x32_bf16 v[84:87], v[178:181], v[212:215], v[84:87]
	v_mfma_f32_16x16x32_bf16 v[80:83], v[188:191], v[212:215], v[80:83]
	v_mfma_f32_16x16x32_bf16 v[68:71], v[178:181], v[220:223], v[68:71]
	v_mfma_f32_16x16x32_bf16 v[64:67], v[188:191], v[220:223], v[64:67]
	v_mfma_f32_16x16x32_bf16 v[246:249], v[232:235], v[192:195], v[246:249]
	v_mfma_f32_16x16x32_bf16 v[246:249], v[236:239], v[196:199], v[246:249]
	s_setprio 0
	s_barrier
	s_add_i32 s56, s50, s39
	v_lshl_add_u64 v[152:153], s[34:35], 0, v[130:131]
	s_mov_b32 m0, s56
	ds_read_b128 v[192:195], v156 offset:16384
	ds_read_b128 v[196:199], v156 offset:17408
	ds_read_b128 v[200:203], v156 offset:18432
	ds_read_b128 v[204:207], v156 offset:19456
	ds_read_b128 v[208:211], v156 offset:20480
	ds_read_b128 v[212:215], v156 offset:21504
	ds_read_b128 v[216:219], v156 offset:22528
	ds_read_b128 v[220:223], v156 offset:23552
	global_load_lds_dwordx4 v[152:153], off
	s_add_i32 m0, s56, 0x2000
	s_add_u32 s56, s34, 0x40000
	v_lshl_add_u64 v[224:225], s[34:35], 0, v[134:135]
	s_addc_u32 s57, s35, 0
	s_add_i32 s58, s51, s39
	global_load_lds_dwordx4 v[224:225], off
	v_lshl_add_u64 v[226:227], s[56:57], 0, v[130:131]
	s_mov_b32 m0, s58
	v_lshl_add_u64 v[228:229], s[36:37], 0, v[132:133]
	global_load_lds_dwordx4 v[226:227], off
	v_lshl_add_u64 v[226:227], s[56:57], 0, v[134:135]
	s_add_i32 m0, s58, 0x2000
	s_nop 0
	global_load_lds_dwordx4 v[226:227], off
	v_lshl_add_u64 v[226:227], s[36:37], 0, v[128:129]
	s_mov_b32 m0, s7
	s_nop 0
	global_load_lds_dwordx4 v[226:227], off
	s_mov_b32 m0, s40
	s_nop 0
	global_load_lds_dwordx4 v[228:229], off
	s_waitcnt vmcnt(10)
	s_waitcnt lgkmcnt(0)
	s_barrier
	s_setprio 1
	s_waitcnt lgkmcnt(0)
	v_mfma_f32_16x16x32_bf16 v[60:63], v[158:161], v[192:195], v[60:63]
	v_mfma_f32_16x16x32_bf16 v[56:59], v[166:169], v[192:195], v[56:59]
	v_mfma_f32_16x16x32_bf16 v[44:47], v[158:161], v[200:203], v[44:47]
	v_mfma_f32_16x16x32_bf16 v[40:43], v[166:169], v[200:203], v[40:43]
	v_mfma_f32_16x16x32_bf16 v[28:31], v[158:161], v[208:211], v[28:31]
	v_mfma_f32_16x16x32_bf16 v[24:27], v[166:169], v[208:211], v[24:27]
	v_mfma_f32_16x16x32_bf16 v[12:15], v[158:161], v[216:219], v[12:15]
	v_mfma_f32_16x16x32_bf16 v[8:11], v[166:169], v[216:219], v[8:11]
	v_mfma_f32_16x16x32_bf16 v[60:63], v[162:165], v[196:199], v[60:63]
	v_mfma_f32_16x16x32_bf16 v[56:59], v[170:173], v[196:199], v[56:59]
	v_mfma_f32_16x16x32_bf16 v[44:47], v[162:165], v[204:207], v[44:47]
	v_mfma_f32_16x16x32_bf16 v[40:43], v[170:173], v[204:207], v[40:43]
	v_mfma_f32_16x16x32_bf16 v[28:31], v[162:165], v[212:215], v[28:31]
	v_mfma_f32_16x16x32_bf16 v[24:27], v[170:173], v[212:215], v[24:27]
	v_mfma_f32_16x16x32_bf16 v[12:15], v[162:165], v[220:223], v[12:15]
	v_mfma_f32_16x16x32_bf16 v[8:11], v[170:173], v[220:223], v[8:11]
	s_setprio 0
	s_setprio 1
	v_mfma_f32_16x16x32_bf16 v[52:55], v[174:177], v[192:195], v[52:55]
	v_mfma_f32_16x16x32_bf16 v[48:51], v[184:187], v[192:195], v[48:51]
	v_mfma_f32_16x16x32_bf16 v[36:39], v[174:177], v[200:203], v[36:39]
	v_mfma_f32_16x16x32_bf16 v[32:35], v[184:187], v[200:203], v[32:35]
	v_mfma_f32_16x16x32_bf16 v[20:23], v[174:177], v[208:211], v[20:23]
	v_mfma_f32_16x16x32_bf16 v[16:19], v[184:187], v[208:211], v[16:19]
	v_mfma_f32_16x16x32_bf16 v[4:7], v[174:177], v[216:219], v[4:7]
	v_mfma_f32_16x16x32_bf16 v[0:3], v[184:187], v[216:219], v[0:3]
	v_mfma_f32_16x16x32_bf16 v[52:55], v[178:181], v[196:199], v[52:55]
	v_mfma_f32_16x16x32_bf16 v[48:51], v[188:191], v[196:199], v[48:51]
	v_mfma_f32_16x16x32_bf16 v[36:39], v[178:181], v[204:207], v[36:39]
	v_mfma_f32_16x16x32_bf16 v[32:35], v[188:191], v[204:207], v[32:35]
	v_mfma_f32_16x16x32_bf16 v[20:23], v[178:181], v[212:215], v[20:23]
	v_mfma_f32_16x16x32_bf16 v[16:19], v[188:191], v[212:215], v[16:19]
	v_mfma_f32_16x16x32_bf16 v[4:7], v[178:181], v[220:223], v[4:7]
	v_mfma_f32_16x16x32_bf16 v[0:3], v[188:191], v[220:223], v[0:3]
	v_mfma_f32_16x16x32_bf16 v[250:253], v[232:235], v[192:195], v[250:253]
	v_mfma_f32_16x16x32_bf16 v[250:253], v[236:239], v[196:199], v[250:253]
	s_setprio 0
	s_barrier
	s_add_i32 s56, 0, 0x18000
	v_add_u32_e32 v136, s56, v145
	s_add_i32 s57, 0, 0x1c000
	ds_read_b128 v[158:161], v136
	ds_read_b128 v[162:165], v136 offset:1024
	ds_read_b128 v[166:169], v136 offset:2048
	ds_read_b128 v[170:173], v136 offset:3072
	v_add_u32_e32 v136, s57, v145
	ds_read_b128 v[174:177], v136
	ds_read_b128 v[178:181], v136 offset:1024
	ds_read_b128 v[184:187], v136 offset:2048
	ds_read_b128 v[188:191], v136 offset:3072
	s_add_u32 s36, s36, 0x40000
	s_addc_u32 s37, s37, 0
	s_mov_b32 m0, s41
	v_lshl_add_u64 v[230:231], s[36:37], 0, v[128:129]
	ds_read_b128 v[192:195], v156 offset:32768
	ds_read_b128 v[196:199], v156 offset:33792
	ds_read_b128 v[200:203], v156 offset:34816
	ds_read_b128 v[204:207], v156 offset:35840
	ds_read_b128 v[208:211], v156 offset:36864
	ds_read_b128 v[212:215], v156 offset:37888
	ds_read_b128 v[216:219], v156 offset:38912
	ds_read_b128 v[220:223], v156 offset:39936
	global_load_lds_dwordx4 v[230:231], off
	v_lshl_add_u64 v[230:231], s[36:37], 0, v[132:133]
	s_mov_b32 m0, s42
	s_nop 0
	global_load_lds_dwordx4 v[230:231], off
	global_load_dwordx4 v[232:235], v245, s[98:99]
	global_load_dwordx4 v[236:239], v245, s[98:99] offset:64
	s_add_u32 s98, s98, 0x80
	s_addc_u32 s99, s99, 0
	s_waitcnt vmcnt(10)
	s_waitcnt lgkmcnt(0)
	s_barrier
	s_setprio 1
	s_waitcnt lgkmcnt(0)
	v_mfma_f32_16x16x32_bf16 v[124:127], v[158:161], v[192:195], v[124:127]
	v_mfma_f32_16x16x32_bf16 v[120:123], v[166:169], v[192:195], v[120:123]
	v_mfma_f32_16x16x32_bf16 v[108:111], v[158:161], v[200:203], v[108:111]
	v_mfma_f32_16x16x32_bf16 v[104:107], v[166:169], v[200:203], v[104:107]
	v_mfma_f32_16x16x32_bf16 v[92:95], v[158:161], v[208:211], v[92:95]
	v_mfma_f32_16x16x32_bf16 v[88:91], v[166:169], v[208:211], v[88:91]
	v_mfma_f32_16x16x32_bf16 v[76:79], v[158:161], v[216:219], v[76:79]
	v_mfma_f32_16x16x32_bf16 v[72:75], v[166:169], v[216:219], v[72:75]
	v_mfma_f32_16x16x32_bf16 v[124:127], v[162:165], v[196:199], v[124:127]
	v_mfma_f32_16x16x32_bf16 v[120:123], v[170:173], v[196:199], v[120:123]
	v_mfma_f32_16x16x32_bf16 v[108:111], v[162:165], v[204:207], v[108:111]
	v_mfma_f32_16x16x32_bf16 v[104:107], v[170:173], v[204:207], v[104:107]
	v_mfma_f32_16x16x32_bf16 v[92:95], v[162:165], v[212:215], v[92:95]
	v_mfma_f32_16x16x32_bf16 v[88:91], v[170:173], v[212:215], v[88:91]
	v_mfma_f32_16x16x32_bf16 v[76:79], v[162:165], v[220:223], v[76:79]
	v_mfma_f32_16x16x32_bf16 v[72:75], v[170:173], v[220:223], v[72:75]
	s_setprio 0
	s_setprio 1
	v_mfma_f32_16x16x32_bf16 v[116:119], v[174:177], v[192:195], v[116:119]
	v_mfma_f32_16x16x32_bf16 v[112:115], v[184:187], v[192:195], v[112:115]
	v_mfma_f32_16x16x32_bf16 v[100:103], v[174:177], v[200:203], v[100:103]
	v_mfma_f32_16x16x32_bf16 v[96:99], v[184:187], v[200:203], v[96:99]
	v_mfma_f32_16x16x32_bf16 v[84:87], v[174:177], v[208:211], v[84:87]
	v_mfma_f32_16x16x32_bf16 v[80:83], v[184:187], v[208:211], v[80:83]
	v_mfma_f32_16x16x32_bf16 v[68:71], v[174:177], v[216:219], v[68:71]
	v_mfma_f32_16x16x32_bf16 v[64:67], v[184:187], v[216:219], v[64:67]
	v_mfma_f32_16x16x32_bf16 v[116:119], v[178:181], v[196:199], v[116:119]
	v_mfma_f32_16x16x32_bf16 v[112:115], v[188:191], v[196:199], v[112:115]
	v_mfma_f32_16x16x32_bf16 v[100:103], v[178:181], v[204:207], v[100:103]
	v_mfma_f32_16x16x32_bf16 v[96:99], v[188:191], v[204:207], v[96:99]
	v_mfma_f32_16x16x32_bf16 v[84:87], v[178:181], v[212:215], v[84:87]
	v_mfma_f32_16x16x32_bf16 v[80:83], v[188:191], v[212:215], v[80:83]
	v_mfma_f32_16x16x32_bf16 v[68:71], v[178:181], v[220:223], v[68:71]
	v_mfma_f32_16x16x32_bf16 v[64:67], v[188:191], v[220:223], v[64:67]
	v_mfma_f32_16x16x32_bf16 v[246:249], v[240:243], v[192:195], v[246:249]
	v_mfma_f32_16x16x32_bf16 v[246:249], v[148:151], v[196:199], v[246:249]
	s_setprio 0
	s_barrier
	s_add_i32 s36, s56, s39
	v_lshl_add_u64 v[152:153], v[152:153], 0, s[12:13]
	s_mov_b32 m0, s36
	ds_read_b128 v[192:195], v156 offset:49152
	ds_read_b128 v[196:199], v156 offset:50176
	ds_read_b128 v[200:203], v156 offset:51200
	ds_read_b128 v[204:207], v156 offset:52224
	ds_read_b128 v[208:211], v156 offset:53248
	ds_read_b128 v[212:215], v156 offset:54272
	ds_read_b128 v[216:219], v156 offset:55296
	ds_read_b128 v[220:223], v156 offset:56320
	global_load_lds_dwordx4 v[152:153], off
	s_add_i32 m0, s36, 0x2000
	s_add_u32 s34, s34, 0x40080
	v_lshl_add_u64 v[152:153], v[224:225], 0, s[12:13]
	s_addc_u32 s35, s35, 0
	s_add_i32 s36, s57, s39
	global_load_lds_dwordx4 v[152:153], off
	v_lshl_add_u64 v[152:153], s[34:35], 0, v[130:131]
	s_mov_b32 m0, s36
	s_nop 0
	global_load_lds_dwordx4 v[152:153], off
	v_lshl_add_u64 v[152:153], s[34:35], 0, v[134:135]
	s_add_i32 m0, s36, 0x2000
	s_nop 0
	global_load_lds_dwordx4 v[152:153], off
	v_lshl_add_u64 v[152:153], v[226:227], 0, s[12:13]
	s_mov_b32 m0, s45
	s_nop 0
	global_load_lds_dwordx4 v[152:153], off
	v_lshl_add_u64 v[152:153], v[228:229], 0, s[12:13]
	s_mov_b32 m0, s46
	s_nop 0
	global_load_lds_dwordx4 v[152:153], off
	s_waitcnt vmcnt(10)
	s_waitcnt lgkmcnt(0)
	s_barrier
	s_setprio 1
	s_waitcnt lgkmcnt(0)
	v_mfma_f32_16x16x32_bf16 v[60:63], v[158:161], v[192:195], v[60:63]
	v_mfma_f32_16x16x32_bf16 v[56:59], v[166:169], v[192:195], v[56:59]
	v_mfma_f32_16x16x32_bf16 v[44:47], v[158:161], v[200:203], v[44:47]
	v_mfma_f32_16x16x32_bf16 v[40:43], v[166:169], v[200:203], v[40:43]
	v_mfma_f32_16x16x32_bf16 v[28:31], v[158:161], v[208:211], v[28:31]
	v_mfma_f32_16x16x32_bf16 v[24:27], v[166:169], v[208:211], v[24:27]
	v_mfma_f32_16x16x32_bf16 v[12:15], v[158:161], v[216:219], v[12:15]
	v_mfma_f32_16x16x32_bf16 v[8:11], v[166:169], v[216:219], v[8:11]
	v_mfma_f32_16x16x32_bf16 v[60:63], v[162:165], v[196:199], v[60:63]
	v_mfma_f32_16x16x32_bf16 v[56:59], v[170:173], v[196:199], v[56:59]
	v_mfma_f32_16x16x32_bf16 v[44:47], v[162:165], v[204:207], v[44:47]
	v_mfma_f32_16x16x32_bf16 v[40:43], v[170:173], v[204:207], v[40:43]
	v_mfma_f32_16x16x32_bf16 v[28:31], v[162:165], v[212:215], v[28:31]
	v_mfma_f32_16x16x32_bf16 v[24:27], v[170:173], v[212:215], v[24:27]
	v_mfma_f32_16x16x32_bf16 v[12:15], v[162:165], v[220:223], v[12:15]
	v_mfma_f32_16x16x32_bf16 v[8:11], v[170:173], v[220:223], v[8:11]
	s_setprio 0
	s_setprio 1
	v_mfma_f32_16x16x32_bf16 v[52:55], v[174:177], v[192:195], v[52:55]
	v_mfma_f32_16x16x32_bf16 v[48:51], v[184:187], v[192:195], v[48:51]
	v_mfma_f32_16x16x32_bf16 v[36:39], v[174:177], v[200:203], v[36:39]
	v_mfma_f32_16x16x32_bf16 v[32:35], v[184:187], v[200:203], v[32:35]
	v_mfma_f32_16x16x32_bf16 v[20:23], v[174:177], v[208:211], v[20:23]
	v_mfma_f32_16x16x32_bf16 v[16:19], v[184:187], v[208:211], v[16:19]
	v_mfma_f32_16x16x32_bf16 v[4:7], v[174:177], v[216:219], v[4:7]
	v_mfma_f32_16x16x32_bf16 v[0:3], v[184:187], v[216:219], v[0:3]
	v_mfma_f32_16x16x32_bf16 v[52:55], v[178:181], v[196:199], v[52:55]
	v_mfma_f32_16x16x32_bf16 v[48:51], v[188:191], v[196:199], v[48:51]
	v_mfma_f32_16x16x32_bf16 v[36:39], v[178:181], v[204:207], v[36:39]
	v_mfma_f32_16x16x32_bf16 v[32:35], v[188:191], v[204:207], v[32:35]
	v_mfma_f32_16x16x32_bf16 v[20:23], v[178:181], v[212:215], v[20:23]
	v_mfma_f32_16x16x32_bf16 v[16:19], v[188:191], v[212:215], v[16:19]
	v_mfma_f32_16x16x32_bf16 v[4:7], v[178:181], v[220:223], v[4:7]
	v_mfma_f32_16x16x32_bf16 v[0:3], v[188:191], v[220:223], v[0:3]
	v_mfma_f32_16x16x32_bf16 v[250:253], v[240:243], v[192:195], v[250:253]
	v_mfma_f32_16x16x32_bf16 v[250:253], v[148:151], v[196:199], v[250:253]
	s_setprio 0
	s_barrier
	s_add_i32 s55, s55, 2
	s_add_u32 s30, s30, 0x100
	s_addc_u32 s31, s31, 0
	s_add_u32 s53, s53, 0x100
	s_addc_u32 s54, s54, 0
	s_cmp_gt_u32 s55, 13
	s_cbranch_scc0 .Ldtf_loop0
	s_branch .Ldtf_exit
.Ldtf_loop1:
	ds_read_b128 v[158:161], v154
	ds_read_b128 v[162:165], v154 offset:1024
	ds_read_b128 v[166:169], v154 offset:2048
	ds_read_b128 v[170:173], v154 offset:3072
	ds_read_b128 v[174:177], v155
	ds_read_b128 v[178:181], v155 offset:1024
	ds_read_b128 v[184:187], v155 offset:2048
	ds_read_b128 v[188:191], v155 offset:3072
	s_add_u32 s34, s30, 0xfffc0080
	s_addc_u32 s35, s31, -1
	s_cmp_eq_u32 s55, 12
	s_cselect_b32 s37, s5, s35
	s_cselect_b32 s36, s8, s34
	s_cselect_b32 s35, s19, s54
	s_cselect_b32 s34, s25, s53
	v_lshl_add_u64 v[152:153], s[30:31], 0, v[142:143]
	s_add_i32 m0, s7, 0xc000
	ds_read_b128 v[192:195], v156
	ds_read_b128 v[196:199], v156 offset:1024
	ds_read_b128 v[200:203], v156 offset:2048
	ds_read_b128 v[204:207], v156 offset:3072
	ds_read_b128 v[208:211], v156 offset:4096
	ds_read_b128 v[212:215], v156 offset:5120
	ds_read_b128 v[216:219], v156 offset:6144
	ds_read_b128 v[220:223], v156 offset:7168
	global_load_lds_dwordx4 v[152:153], off
	v_lshl_add_u64 v[152:153], s[30:31], 0, v[146:147]
	s_add_i32 m0, s7, 0xe000
	s_nop 0
	global_load_lds_dwordx4 v[152:153], off
	global_load_dwordx4 v[240:243], v245, s[98:99]
	global_load_dwordx4 v[148:151], v245, s[98:99] offset:64
	s_add_u32 s98, s98, 0x80
	s_addc_u32 s99, s99, 0
	s_waitcnt vmcnt(10)
	s_waitcnt lgkmcnt(0)
	s_barrier
	s_setprio 1
	s_waitcnt lgkmcnt(0)
	v_mfma_f32_16x16x32_bf16 v[124:127], v[158:161], v[192:195], v[124:127]
	v_mfma_f32_16x16x32_bf16 v[120:123], v[166:169], v[192:195], v[120:123]
	v_mfma_f32_16x16x32_bf16 v[108:111], v[158:161], v[200:203], v[108:111]
	v_mfma_f32_16x16x32_bf16 v[104:107], v[166:169], v[200:203], v[104:107]
	v_mfma_f32_16x16x32_bf16 v[92:95], v[158:161], v[208:211], v[92:95]
	v_mfma_f32_16x16x32_bf16 v[88:91], v[166:169], v[208:211], v[88:91]
	v_mfma_f32_16x16x32_bf16 v[76:79], v[158:161], v[216:219], v[76:79]
	v_mfma_f32_16x16x32_bf16 v[72:75], v[166:169], v[216:219], v[72:75]
	v_mfma_f32_16x16x32_bf16 v[124:127], v[162:165], v[196:199], v[124:127]
	v_mfma_f32_16x16x32_bf16 v[120:123], v[170:173], v[196:199], v[120:123]
	v_mfma_f32_16x16x32_bf16 v[108:111], v[162:165], v[204:207], v[108:111]
	v_mfma_f32_16x16x32_bf16 v[104:107], v[170:173], v[204:207], v[104:107]
	v_mfma_f32_16x16x32_bf16 v[92:95], v[162:165], v[212:215], v[92:95]
	v_mfma_f32_16x16x32_bf16 v[88:91], v[170:173], v[212:215], v[88:91]
	v_mfma_f32_16x16x32_bf16 v[76:79], v[162:165], v[220:223], v[76:79]
	v_mfma_f32_16x16x32_bf16 v[72:75], v[170:173], v[220:223], v[72:75]
	s_setprio 0
	s_setprio 1
	v_mfma_f32_16x16x32_bf16 v[116:119], v[174:177], v[192:195], v[116:119]
	v_mfma_f32_16x16x32_bf16 v[112:115], v[184:187], v[192:195], v[112:115]
	v_mfma_f32_16x16x32_bf16 v[100:103], v[174:177], v[200:203], v[100:103]
	v_mfma_f32_16x16x32_bf16 v[96:99], v[184:187], v[200:203], v[96:99]
	v_mfma_f32_16x16x32_bf16 v[84:87], v[174:177], v[208:211], v[84:87]
	v_mfma_f32_16x16x32_bf16 v[80:83], v[184:187], v[208:211], v[80:83]
	v_mfma_f32_16x16x32_bf16 v[68:71], v[174:177], v[216:219], v[68:71]
	v_mfma_f32_16x16x32_bf16 v[64:67], v[184:187], v[216:219], v[64:67]
	v_mfma_f32_16x16x32_bf16 v[116:119], v[178:181], v[196:199], v[116:119]
	v_mfma_f32_16x16x32_bf16 v[112:115], v[188:191], v[196:199], v[112:115]
	v_mfma_f32_16x16x32_bf16 v[100:103], v[178:181], v[204:207], v[100:103]
	v_mfma_f32_16x16x32_bf16 v[96:99], v[188:191], v[204:207], v[96:99]
	v_mfma_f32_16x16x32_bf16 v[84:87], v[178:181], v[212:215], v[84:87]
	v_mfma_f32_16x16x32_bf16 v[80:83], v[188:191], v[212:215], v[80:83]
	v_mfma_f32_16x16x32_bf16 v[68:71], v[178:181], v[220:223], v[68:71]
	v_mfma_f32_16x16x32_bf16 v[64:67], v[188:191], v[220:223], v[64:67]
	v_mfma_f32_16x16x32_bf16 v[246:249], v[232:235], v[200:203], v[246:249]
	v_mfma_f32_16x16x32_bf16 v[246:249], v[236:239], v[204:207], v[246:249]
	s_setprio 0
	s_barrier
	s_add_i32 s56, s50, s39
	v_lshl_add_u64 v[152:153], s[34:35], 0, v[130:131]
	s_mov_b32 m0, s56
	ds_read_b128 v[192:195], v156 offset:16384
	ds_read_b128 v[196:199], v156 offset:17408
	ds_read_b128 v[200:203], v156 offset:18432
	ds_read_b128 v[204:207], v156 offset:19456
	ds_read_b128 v[208:211], v156 offset:20480
	ds_read_b128 v[212:215], v156 offset:21504
	ds_read_b128 v[216:219], v156 offset:22528
	ds_read_b128 v[220:223], v156 offset:23552
	global_load_lds_dwordx4 v[152:153], off
	s_add_i32 m0, s56, 0x2000
	s_add_u32 s56, s34, 0x40000
	v_lshl_add_u64 v[224:225], s[34:35], 0, v[134:135]
	s_addc_u32 s57, s35, 0
	s_add_i32 s58, s51, s39
	global_load_lds_dwordx4 v[224:225], off
	v_lshl_add_u64 v[226:227], s[56:57], 0, v[130:131]
	s_mov_b32 m0, s58
	v_lshl_add_u64 v[228:229], s[36:37], 0, v[132:133]
	global_load_lds_dwordx4 v[226:227], off
	v_lshl_add_u64 v[226:227], s[56:57], 0, v[134:135]
	s_add_i32 m0, s58, 0x2000
	s_nop 0
	global_load_lds_dwordx4 v[226:227], off
	v_lshl_add_u64 v[226:227], s[36:37], 0, v[128:129]
	s_mov_b32 m0, s7
	s_nop 0
	global_load_lds_dwordx4 v[226:227], off
	s_mov_b32 m0, s40
	s_nop 0
	global_load_lds_dwordx4 v[228:229], off
	s_waitcnt vmcnt(10)
	s_waitcnt lgkmcnt(0)
	s_barrier
	s_setprio 1
	s_waitcnt lgkmcnt(0)
	v_mfma_f32_16x16x32_bf16 v[60:63], v[158:161], v[192:195], v[60:63]
	v_mfma_f32_16x16x32_bf16 v[56:59], v[166:169], v[192:195], v[56:59]
	v_mfma_f32_16x16x32_bf16 v[44:47], v[158:161], v[200:203], v[44:47]
	v_mfma_f32_16x16x32_bf16 v[40:43], v[166:169], v[200:203], v[40:43]
	v_mfma_f32_16x16x32_bf16 v[28:31], v[158:161], v[208:211], v[28:31]
	v_mfma_f32_16x16x32_bf16 v[24:27], v[166:169], v[208:211], v[24:27]
	v_mfma_f32_16x16x32_bf16 v[12:15], v[158:161], v[216:219], v[12:15]
	v_mfma_f32_16x16x32_bf16 v[8:11], v[166:169], v[216:219], v[8:11]
	v_mfma_f32_16x16x32_bf16 v[60:63], v[162:165], v[196:199], v[60:63]
	v_mfma_f32_16x16x32_bf16 v[56:59], v[170:173], v[196:199], v[56:59]
	v_mfma_f32_16x16x32_bf16 v[44:47], v[162:165], v[204:207], v[44:47]
	v_mfma_f32_16x16x32_bf16 v[40:43], v[170:173], v[204:207], v[40:43]
	v_mfma_f32_16x16x32_bf16 v[28:31], v[162:165], v[212:215], v[28:31]
	v_mfma_f32_16x16x32_bf16 v[24:27], v[170:173], v[212:215], v[24:27]
	v_mfma_f32_16x16x32_bf16 v[12:15], v[162:165], v[220:223], v[12:15]
	v_mfma_f32_16x16x32_bf16 v[8:11], v[170:173], v[220:223], v[8:11]
	s_setprio 0
	s_setprio 1
	v_mfma_f32_16x16x32_bf16 v[52:55], v[174:177], v[192:195], v[52:55]
	v_mfma_f32_16x16x32_bf16 v[48:51], v[184:187], v[192:195], v[48:51]
	v_mfma_f32_16x16x32_bf16 v[36:39], v[174:177], v[200:203], v[36:39]
	v_mfma_f32_16x16x32_bf16 v[32:35], v[184:187], v[200:203], v[32:35]
	v_mfma_f32_16x16x32_bf16 v[20:23], v[174:177], v[208:211], v[20:23]
	v_mfma_f32_16x16x32_bf16 v[16:19], v[184:187], v[208:211], v[16:19]
	v_mfma_f32_16x16x32_bf16 v[4:7], v[174:177], v[216:219], v[4:7]
	v_mfma_f32_16x16x32_bf16 v[0:3], v[184:187], v[216:219], v[0:3]
	v_mfma_f32_16x16x32_bf16 v[52:55], v[178:181], v[196:199], v[52:55]
	v_mfma_f32_16x16x32_bf16 v[48:51], v[188:191], v[196:199], v[48:51]
	v_mfma_f32_16x16x32_bf16 v[36:39], v[178:181], v[204:207], v[36:39]
	v_mfma_f32_16x16x32_bf16 v[32:35], v[188:191], v[204:207], v[32:35]
	v_mfma_f32_16x16x32_bf16 v[20:23], v[178:181], v[212:215], v[20:23]
	v_mfma_f32_16x16x32_bf16 v[16:19], v[188:191], v[212:215], v[16:19]
	v_mfma_f32_16x16x32_bf16 v[4:7], v[178:181], v[220:223], v[4:7]
	v_mfma_f32_16x16x32_bf16 v[0:3], v[188:191], v[220:223], v[0:3]
	v_mfma_f32_16x16x32_bf16 v[250:253], v[232:235], v[200:203], v[250:253]
	v_mfma_f32_16x16x32_bf16 v[250:253], v[236:239], v[204:207], v[250:253]
	s_setprio 0
	s_barrier
	s_add_i32 s56, 0, 0x18000
	v_add_u32_e32 v136, s56, v145
	s_add_i32 s57, 0, 0x1c000
	ds_read_b128 v[158:161], v136
	ds_read_b128 v[162:165], v136 offset:1024
	ds_read_b128 v[166:169], v136 offset:2048
	ds_read_b128 v[170:173], v136 offset:3072
	v_add_u32_e32 v136, s57, v145
	ds_read_b128 v[174:177], v136
	ds_read_b128 v[178:181], v136 offset:1024
	ds_read_b128 v[184:187], v136 offset:2048
	ds_read_b128 v[188:191], v136 offset:3072
	s_add_u32 s36, s36, 0x40000
	s_addc_u32 s37, s37, 0
	s_mov_b32 m0, s41
	v_lshl_add_u64 v[230:231], s[36:37], 0, v[128:129]
	ds_read_b128 v[192:195], v156 offset:32768
	ds_read_b128 v[196:199], v156 offset:33792
	ds_read_b128 v[200:203], v156 offset:34816
	ds_read_b128 v[204:207], v156 offset:35840
	ds_read_b128 v[208:211], v156 offset:36864
	ds_read_b128 v[212:215], v156 offset:37888
	ds_read_b128 v[216:219], v156 offset:38912
	ds_read_b128 v[220:223], v156 offset:39936
	global_load_lds_dwordx4 v[230:231], off
	v_lshl_add_u64 v[230:231], s[36:37], 0, v[132:133]
	s_mov_b32 m0, s42
	s_nop 0
	global_load_lds_dwordx4 v[230:231], off
	global_load_dwordx4 v[232:235], v245, s[98:99]
	global_load_dwordx4 v[236:239], v245, s[98:99] offset:64
	s_add_u32 s98, s98, 0x80
	s_addc_u32 s99, s99, 0
	s_waitcnt vmcnt(10)
	s_waitcnt lgkmcnt(0)
	s_barrier
	s_setprio 1
	s_waitcnt lgkmcnt(0)
	v_mfma_f32_16x16x32_bf16 v[124:127], v[158:161], v[192:195], v[124:127]
	v_mfma_f32_16x16x32_bf16 v[120:123], v[166:169], v[192:195], v[120:123]
	v_mfma_f32_16x16x32_bf16 v[108:111], v[158:161], v[200:203], v[108:111]
	v_mfma_f32_16x16x32_bf16 v[104:107], v[166:169], v[200:203], v[104:107]
	v_mfma_f32_16x16x32_bf16 v[92:95], v[158:161], v[208:211], v[92:95]
	v_mfma_f32_16x16x32_bf16 v[88:91], v[166:169], v[208:211], v[88:91]
	v_mfma_f32_16x16x32_bf16 v[76:79], v[158:161], v[216:219], v[76:79]
	v_mfma_f32_16x16x32_bf16 v[72:75], v[166:169], v[216:219], v[72:75]
	v_mfma_f32_16x16x32_bf16 v[124:127], v[162:165], v[196:199], v[124:127]
	v_mfma_f32_16x16x32_bf16 v[120:123], v[170:173], v[196:199], v[120:123]
	v_mfma_f32_16x16x32_bf16 v[108:111], v[162:165], v[204:207], v[108:111]
	v_mfma_f32_16x16x32_bf16 v[104:107], v[170:173], v[204:207], v[104:107]
	v_mfma_f32_16x16x32_bf16 v[92:95], v[162:165], v[212:215], v[92:95]
	v_mfma_f32_16x16x32_bf16 v[88:91], v[170:173], v[212:215], v[88:91]
	v_mfma_f32_16x16x32_bf16 v[76:79], v[162:165], v[220:223], v[76:79]
	v_mfma_f32_16x16x32_bf16 v[72:75], v[170:173], v[220:223], v[72:75]
	s_setprio 0
	s_setprio 1
	v_mfma_f32_16x16x32_bf16 v[116:119], v[174:177], v[192:195], v[116:119]
	v_mfma_f32_16x16x32_bf16 v[112:115], v[184:187], v[192:195], v[112:115]
	v_mfma_f32_16x16x32_bf16 v[100:103], v[174:177], v[200:203], v[100:103]
	v_mfma_f32_16x16x32_bf16 v[96:99], v[184:187], v[200:203], v[96:99]
	v_mfma_f32_16x16x32_bf16 v[84:87], v[174:177], v[208:211], v[84:87]
	v_mfma_f32_16x16x32_bf16 v[80:83], v[184:187], v[208:211], v[80:83]
	v_mfma_f32_16x16x32_bf16 v[68:71], v[174:177], v[216:219], v[68:71]
	v_mfma_f32_16x16x32_bf16 v[64:67], v[184:187], v[216:219], v[64:67]
	v_mfma_f32_16x16x32_bf16 v[116:119], v[178:181], v[196:199], v[116:119]
	v_mfma_f32_16x16x32_bf16 v[112:115], v[188:191], v[196:199], v[112:115]
	v_mfma_f32_16x16x32_bf16 v[100:103], v[178:181], v[204:207], v[100:103]
	v_mfma_f32_16x16x32_bf16 v[96:99], v[188:191], v[204:207], v[96:99]
	v_mfma_f32_16x16x32_bf16 v[84:87], v[178:181], v[212:215], v[84:87]
	v_mfma_f32_16x16x32_bf16 v[80:83], v[188:191], v[212:215], v[80:83]
	v_mfma_f32_16x16x32_bf16 v[68:71], v[178:181], v[220:223], v[68:71]
	v_mfma_f32_16x16x32_bf16 v[64:67], v[188:191], v[220:223], v[64:67]
	v_mfma_f32_16x16x32_bf16 v[246:249], v[240:243], v[200:203], v[246:249]
	v_mfma_f32_16x16x32_bf16 v[246:249], v[148:151], v[204:207], v[246:249]
	s_setprio 0
	s_barrier
	s_add_i32 s36, s56, s39
	v_lshl_add_u64 v[152:153], v[152:153], 0, s[12:13]
	s_mov_b32 m0, s36
	ds_read_b128 v[192:195], v156 offset:49152
	ds_read_b128 v[196:199], v156 offset:50176
	ds_read_b128 v[200:203], v156 offset:51200
	ds_read_b128 v[204:207], v156 offset:52224
	ds_read_b128 v[208:211], v156 offset:53248
	ds_read_b128 v[212:215], v156 offset:54272
	ds_read_b128 v[216:219], v156 offset:55296
	ds_read_b128 v[220:223], v156 offset:56320
	global_load_lds_dwordx4 v[152:153], off
	s_add_i32 m0, s36, 0x2000
	s_add_u32 s34, s34, 0x40080
	v_lshl_add_u64 v[152:153], v[224:225], 0, s[12:13]
	s_addc_u32 s35, s35, 0
	s_add_i32 s36, s57, s39
	global_load_lds_dwordx4 v[152:153], off
	v_lshl_add_u64 v[152:153], s[34:35], 0, v[130:131]
	s_mov_b32 m0, s36
	s_nop 0
	global_load_lds_dwordx4 v[152:153], off
	v_lshl_add_u64 v[152:153], s[34:35], 0, v[134:135]
	s_add_i32 m0, s36, 0x2000
	s_nop 0
	global_load_lds_dwordx4 v[152:153], off
	v_lshl_add_u64 v[152:153], v[226:227], 0, s[12:13]
	s_mov_b32 m0, s45
	s_nop 0
	global_load_lds_dwordx4 v[152:153], off
	v_lshl_add_u64 v[152:153], v[228:229], 0, s[12:13]
	s_mov_b32 m0, s46
	s_nop 0
	global_load_lds_dwordx4 v[152:153], off
	s_waitcnt vmcnt(10)
	s_waitcnt lgkmcnt(0)
	s_barrier
	s_setprio 1
	s_waitcnt lgkmcnt(0)
	v_mfma_f32_16x16x32_bf16 v[60:63], v[158:161], v[192:195], v[60:63]
	v_mfma_f32_16x16x32_bf16 v[56:59], v[166:169], v[192:195], v[56:59]
	v_mfma_f32_16x16x32_bf16 v[44:47], v[158:161], v[200:203], v[44:47]
	v_mfma_f32_16x16x32_bf16 v[40:43], v[166:169], v[200:203], v[40:43]
	v_mfma_f32_16x16x32_bf16 v[28:31], v[158:161], v[208:211], v[28:31]
	v_mfma_f32_16x16x32_bf16 v[24:27], v[166:169], v[208:211], v[24:27]
	v_mfma_f32_16x16x32_bf16 v[12:15], v[158:161], v[216:219], v[12:15]
	v_mfma_f32_16x16x32_bf16 v[8:11], v[166:169], v[216:219], v[8:11]
	v_mfma_f32_16x16x32_bf16 v[60:63], v[162:165], v[196:199], v[60:63]
	v_mfma_f32_16x16x32_bf16 v[56:59], v[170:173], v[196:199], v[56:59]
	v_mfma_f32_16x16x32_bf16 v[44:47], v[162:165], v[204:207], v[44:47]
	v_mfma_f32_16x16x32_bf16 v[40:43], v[170:173], v[204:207], v[40:43]
	v_mfma_f32_16x16x32_bf16 v[28:31], v[162:165], v[212:215], v[28:31]
	v_mfma_f32_16x16x32_bf16 v[24:27], v[170:173], v[212:215], v[24:27]
	v_mfma_f32_16x16x32_bf16 v[12:15], v[162:165], v[220:223], v[12:15]
	v_mfma_f32_16x16x32_bf16 v[8:11], v[170:173], v[220:223], v[8:11]
	s_setprio 0
	s_setprio 1
	v_mfma_f32_16x16x32_bf16 v[52:55], v[174:177], v[192:195], v[52:55]
	v_mfma_f32_16x16x32_bf16 v[48:51], v[184:187], v[192:195], v[48:51]
	v_mfma_f32_16x16x32_bf16 v[36:39], v[174:177], v[200:203], v[36:39]
	v_mfma_f32_16x16x32_bf16 v[32:35], v[184:187], v[200:203], v[32:35]
	v_mfma_f32_16x16x32_bf16 v[20:23], v[174:177], v[208:211], v[20:23]
	v_mfma_f32_16x16x32_bf16 v[16:19], v[184:187], v[208:211], v[16:19]
	v_mfma_f32_16x16x32_bf16 v[4:7], v[174:177], v[216:219], v[4:7]
	v_mfma_f32_16x16x32_bf16 v[0:3], v[184:187], v[216:219], v[0:3]
	v_mfma_f32_16x16x32_bf16 v[52:55], v[178:181], v[196:199], v[52:55]
	v_mfma_f32_16x16x32_bf16 v[48:51], v[188:191], v[196:199], v[48:51]
	v_mfma_f32_16x16x32_bf16 v[36:39], v[178:181], v[204:207], v[36:39]
	v_mfma_f32_16x16x32_bf16 v[32:35], v[188:191], v[204:207], v[32:35]
	v_mfma_f32_16x16x32_bf16 v[20:23], v[178:181], v[212:215], v[20:23]
	v_mfma_f32_16x16x32_bf16 v[16:19], v[188:191], v[212:215], v[16:19]
	v_mfma_f32_16x16x32_bf16 v[4:7], v[178:181], v[220:223], v[4:7]
	v_mfma_f32_16x16x32_bf16 v[0:3], v[188:191], v[220:223], v[0:3]
	v_mfma_f32_16x16x32_bf16 v[250:253], v[240:243], v[200:203], v[250:253]
	v_mfma_f32_16x16x32_bf16 v[250:253], v[148:151], v[204:207], v[250:253]
	s_setprio 0
	s_barrier
	s_add_i32 s55, s55, 2
	s_add_u32 s30, s30, 0x100
	s_addc_u32 s31, s31, 0
	s_add_u32 s53, s53, 0x100
	s_addc_u32 s54, s54, 0
	s_cmp_gt_u32 s55, 13
	s_cbranch_scc0 .Ldtf_loop1
	s_branch .Ldtf_exit
.Ldtf_loop2:
	ds_read_b128 v[158:161], v154
	ds_read_b128 v[162:165], v154 offset:1024
	ds_read_b128 v[166:169], v154 offset:2048
	ds_read_b128 v[170:173], v154 offset:3072
	ds_read_b128 v[174:177], v155
	ds_read_b128 v[178:181], v155 offset:1024
	ds_read_b128 v[184:187], v155 offset:2048
	ds_read_b128 v[188:191], v155 offset:3072
	s_add_u32 s34, s30, 0xfffc0080
	s_addc_u32 s35, s31, -1
	s_cmp_eq_u32 s55, 12
	s_cselect_b32 s37, s5, s35
	s_cselect_b32 s36, s8, s34
	s_cselect_b32 s35, s19, s54
	s_cselect_b32 s34, s25, s53
	v_lshl_add_u64 v[152:153], s[30:31], 0, v[142:143]
	s_add_i32 m0, s7, 0xc000
	ds_read_b128 v[192:195], v156
	ds_read_b128 v[196:199], v156 offset:1024
	ds_read_b128 v[200:203], v156 offset:2048
	ds_read_b128 v[204:207], v156 offset:3072
	ds_read_b128 v[208:211], v156 offset:4096
	ds_read_b128 v[212:215], v156 offset:5120
	ds_read_b128 v[216:219], v156 offset:6144
	ds_read_b128 v[220:223], v156 offset:7168
	global_load_lds_dwordx4 v[152:153], off
	v_lshl_add_u64 v[152:153], s[30:31], 0, v[146:147]
	s_add_i32 m0, s7, 0xe000
	s_nop 0
	global_load_lds_dwordx4 v[152:153], off
	global_load_dwordx4 v[240:243], v245, s[98:99]
	global_load_dwordx4 v[148:151], v245, s[98:99] offset:64
	s_add_u32 s98, s98, 0x80
	s_addc_u32 s99, s99, 0
	s_waitcnt vmcnt(10)
	s_waitcnt lgkmcnt(0)
	s_barrier
	s_setprio 1
	s_waitcnt lgkmcnt(0)
	v_mfma_f32_16x16x32_bf16 v[124:127], v[158:161], v[192:195], v[124:127]
	v_mfma_f32_16x16x32_bf16 v[120:123], v[166:169], v[192:195], v[120:123]
	v_mfma_f32_16x16x32_bf16 v[108:111], v[158:161], v[200:203], v[108:111]
	v_mfma_f32_16x16x32_bf16 v[104:107], v[166:169], v[200:203], v[104:107]
	v_mfma_f32_16x16x32_bf16 v[92:95], v[158:161], v[208:211], v[92:95]
	v_mfma_f32_16x16x32_bf16 v[88:91], v[166:169], v[208:211], v[88:91]
	v_mfma_f32_16x16x32_bf16 v[76:79], v[158:161], v[216:219], v[76:79]
	v_mfma_f32_16x16x32_bf16 v[72:75], v[166:169], v[216:219], v[72:75]
	v_mfma_f32_16x16x32_bf16 v[124:127], v[162:165], v[196:199], v[124:127]
	v_mfma_f32_16x16x32_bf16 v[120:123], v[170:173], v[196:199], v[120:123]
	v_mfma_f32_16x16x32_bf16 v[108:111], v[162:165], v[204:207], v[108:111]
	v_mfma_f32_16x16x32_bf16 v[104:107], v[170:173], v[204:207], v[104:107]
	v_mfma_f32_16x16x32_bf16 v[92:95], v[162:165], v[212:215], v[92:95]
	v_mfma_f32_16x16x32_bf16 v[88:91], v[170:173], v[212:215], v[88:91]
	v_mfma_f32_16x16x32_bf16 v[76:79], v[162:165], v[220:223], v[76:79]
	v_mfma_f32_16x16x32_bf16 v[72:75], v[170:173], v[220:223], v[72:75]
	s_setprio 0
	s_setprio 1
	v_mfma_f32_16x16x32_bf16 v[116:119], v[174:177], v[192:195], v[116:119]
	v_mfma_f32_16x16x32_bf16 v[112:115], v[184:187], v[192:195], v[112:115]
	v_mfma_f32_16x16x32_bf16 v[100:103], v[174:177], v[200:203], v[100:103]
	v_mfma_f32_16x16x32_bf16 v[96:99], v[184:187], v[200:203], v[96:99]
	v_mfma_f32_16x16x32_bf16 v[84:87], v[174:177], v[208:211], v[84:87]
	v_mfma_f32_16x16x32_bf16 v[80:83], v[184:187], v[208:211], v[80:83]
	v_mfma_f32_16x16x32_bf16 v[68:71], v[174:177], v[216:219], v[68:71]
	v_mfma_f32_16x16x32_bf16 v[64:67], v[184:187], v[216:219], v[64:67]
	v_mfma_f32_16x16x32_bf16 v[116:119], v[178:181], v[196:199], v[116:119]
	v_mfma_f32_16x16x32_bf16 v[112:115], v[188:191], v[196:199], v[112:115]
	v_mfma_f32_16x16x32_bf16 v[100:103], v[178:181], v[204:207], v[100:103]
	v_mfma_f32_16x16x32_bf16 v[96:99], v[188:191], v[204:207], v[96:99]
	v_mfma_f32_16x16x32_bf16 v[84:87], v[178:181], v[212:215], v[84:87]
	v_mfma_f32_16x16x32_bf16 v[80:83], v[188:191], v[212:215], v[80:83]
	v_mfma_f32_16x16x32_bf16 v[68:71], v[178:181], v[220:223], v[68:71]
	v_mfma_f32_16x16x32_bf16 v[64:67], v[188:191], v[220:223], v[64:67]
	v_mfma_f32_16x16x32_bf16 v[246:249], v[232:235], v[208:211], v[246:249]
	v_mfma_f32_16x16x32_bf16 v[246:249], v[236:239], v[212:215], v[246:249]
	s_setprio 0
	s_barrier
	s_add_i32 s56, s50, s39
	v_lshl_add_u64 v[152:153], s[34:35], 0, v[130:131]
	s_mov_b32 m0, s56
	ds_read_b128 v[192:195], v156 offset:16384
	ds_read_b128 v[196:199], v156 offset:17408
	ds_read_b128 v[200:203], v156 offset:18432
	ds_read_b128 v[204:207], v156 offset:19456
	ds_read_b128 v[208:211], v156 offset:20480
	ds_read_b128 v[212:215], v156 offset:21504
	ds_read_b128 v[216:219], v156 offset:22528
	ds_read_b128 v[220:223], v156 offset:23552
	global_load_lds_dwordx4 v[152:153], off
	s_add_i32 m0, s56, 0x2000
	s_add_u32 s56, s34, 0x40000
	v_lshl_add_u64 v[224:225], s[34:35], 0, v[134:135]
	s_addc_u32 s57, s35, 0
	s_add_i32 s58, s51, s39
	global_load_lds_dwordx4 v[224:225], off
	v_lshl_add_u64 v[226:227], s[56:57], 0, v[130:131]
	s_mov_b32 m0, s58
	v_lshl_add_u64 v[228:229], s[36:37], 0, v[132:133]
	global_load_lds_dwordx4 v[226:227], off
	v_lshl_add_u64 v[226:227], s[56:57], 0, v[134:135]
	s_add_i32 m0, s58, 0x2000
	s_nop 0
	global_load_lds_dwordx4 v[226:227], off
	v_lshl_add_u64 v[226:227], s[36:37], 0, v[128:129]
	s_mov_b32 m0, s7
	s_nop 0
	global_load_lds_dwordx4 v[226:227], off
	s_mov_b32 m0, s40
	s_nop 0
	global_load_lds_dwordx4 v[228:229], off
	s_waitcnt vmcnt(10)
	s_waitcnt lgkmcnt(0)
	s_barrier
	s_setprio 1
	s_waitcnt lgkmcnt(0)
	v_mfma_f32_16x16x32_bf16 v[60:63], v[158:161], v[192:195], v[60:63]
	v_mfma_f32_16x16x32_bf16 v[56:59], v[166:169], v[192:195], v[56:59]
	v_mfma_f32_16x16x32_bf16 v[44:47], v[158:161], v[200:203], v[44:47]
	v_mfma_f32_16x16x32_bf16 v[40:43], v[166:169], v[200:203], v[40:43]
	v_mfma_f32_16x16x32_bf16 v[28:31], v[158:161], v[208:211], v[28:31]
	v_mfma_f32_16x16x32_bf16 v[24:27], v[166:169], v[208:211], v[24:27]
	v_mfma_f32_16x16x32_bf16 v[12:15], v[158:161], v[216:219], v[12:15]
	v_mfma_f32_16x16x32_bf16 v[8:11], v[166:169], v[216:219], v[8:11]
	v_mfma_f32_16x16x32_bf16 v[60:63], v[162:165], v[196:199], v[60:63]
	v_mfma_f32_16x16x32_bf16 v[56:59], v[170:173], v[196:199], v[56:59]
	v_mfma_f32_16x16x32_bf16 v[44:47], v[162:165], v[204:207], v[44:47]
	v_mfma_f32_16x16x32_bf16 v[40:43], v[170:173], v[204:207], v[40:43]
	v_mfma_f32_16x16x32_bf16 v[28:31], v[162:165], v[212:215], v[28:31]
	v_mfma_f32_16x16x32_bf16 v[24:27], v[170:173], v[212:215], v[24:27]
	v_mfma_f32_16x16x32_bf16 v[12:15], v[162:165], v[220:223], v[12:15]
	v_mfma_f32_16x16x32_bf16 v[8:11], v[170:173], v[220:223], v[8:11]
	s_setprio 0
	s_setprio 1
	v_mfma_f32_16x16x32_bf16 v[52:55], v[174:177], v[192:195], v[52:55]
	v_mfma_f32_16x16x32_bf16 v[48:51], v[184:187], v[192:195], v[48:51]
	v_mfma_f32_16x16x32_bf16 v[36:39], v[174:177], v[200:203], v[36:39]
	v_mfma_f32_16x16x32_bf16 v[32:35], v[184:187], v[200:203], v[32:35]
	v_mfma_f32_16x16x32_bf16 v[20:23], v[174:177], v[208:211], v[20:23]
	v_mfma_f32_16x16x32_bf16 v[16:19], v[184:187], v[208:211], v[16:19]
	v_mfma_f32_16x16x32_bf16 v[4:7], v[174:177], v[216:219], v[4:7]
	v_mfma_f32_16x16x32_bf16 v[0:3], v[184:187], v[216:219], v[0:3]
	v_mfma_f32_16x16x32_bf16 v[52:55], v[178:181], v[196:199], v[52:55]
	v_mfma_f32_16x16x32_bf16 v[48:51], v[188:191], v[196:199], v[48:51]
	v_mfma_f32_16x16x32_bf16 v[36:39], v[178:181], v[204:207], v[36:39]
	v_mfma_f32_16x16x32_bf16 v[32:35], v[188:191], v[204:207], v[32:35]
	v_mfma_f32_16x16x32_bf16 v[20:23], v[178:181], v[212:215], v[20:23]
	v_mfma_f32_16x16x32_bf16 v[16:19], v[188:191], v[212:215], v[16:19]
	v_mfma_f32_16x16x32_bf16 v[4:7], v[178:181], v[220:223], v[4:7]
	v_mfma_f32_16x16x32_bf16 v[0:3], v[188:191], v[220:223], v[0:3]
	v_mfma_f32_16x16x32_bf16 v[250:253], v[232:235], v[208:211], v[250:253]
	v_mfma_f32_16x16x32_bf16 v[250:253], v[236:239], v[212:215], v[250:253]
	s_setprio 0
	s_barrier
	s_add_i32 s56, 0, 0x18000
	v_add_u32_e32 v136, s56, v145
	s_add_i32 s57, 0, 0x1c000
	ds_read_b128 v[158:161], v136
	ds_read_b128 v[162:165], v136 offset:1024
	ds_read_b128 v[166:169], v136 offset:2048
	ds_read_b128 v[170:173], v136 offset:3072
	v_add_u32_e32 v136, s57, v145
	ds_read_b128 v[174:177], v136
	ds_read_b128 v[178:181], v136 offset:1024
	ds_read_b128 v[184:187], v136 offset:2048
	ds_read_b128 v[188:191], v136 offset:3072
	s_add_u32 s36, s36, 0x40000
	s_addc_u32 s37, s37, 0
	s_mov_b32 m0, s41
	v_lshl_add_u64 v[230:231], s[36:37], 0, v[128:129]
	ds_read_b128 v[192:195], v156 offset:32768
	ds_read_b128 v[196:199], v156 offset:33792
	ds_read_b128 v[200:203], v156 offset:34816
	ds_read_b128 v[204:207], v156 offset:35840
	ds_read_b128 v[208:211], v156 offset:36864
	ds_read_b128 v[212:215], v156 offset:37888
	ds_read_b128 v[216:219], v156 offset:38912
	ds_read_b128 v[220:223], v156 offset:39936
	global_load_lds_dwordx4 v[230:231], off
	v_lshl_add_u64 v[230:231], s[36:37], 0, v[132:133]
	s_mov_b32 m0, s42
	s_nop 0
	global_load_lds_dwordx4 v[230:231], off
	global_load_dwordx4 v[232:235], v245, s[98:99]
	global_load_dwordx4 v[236:239], v245, s[98:99] offset:64
	s_add_u32 s98, s98, 0x80
	s_addc_u32 s99, s99, 0
	s_waitcnt vmcnt(10)
	s_waitcnt lgkmcnt(0)
	s_barrier
	s_setprio 1
	s_waitcnt lgkmcnt(0)
	v_mfma_f32_16x16x32_bf16 v[124:127], v[158:161], v[192:195], v[124:127]
	v_mfma_f32_16x16x32_bf16 v[120:123], v[166:169], v[192:195], v[120:123]
	v_mfma_f32_16x16x32_bf16 v[108:111], v[158:161], v[200:203], v[108:111]
	v_mfma_f32_16x16x32_bf16 v[104:107], v[166:169], v[200:203], v[104:107]
	v_mfma_f32_16x16x32_bf16 v[92:95], v[158:161], v[208:211], v[92:95]
	v_mfma_f32_16x16x32_bf16 v[88:91], v[166:169], v[208:211], v[88:91]
	v_mfma_f32_16x16x32_bf16 v[76:79], v[158:161], v[216:219], v[76:79]
	v_mfma_f32_16x16x32_bf16 v[72:75], v[166:169], v[216:219], v[72:75]
	v_mfma_f32_16x16x32_bf16 v[124:127], v[162:165], v[196:199], v[124:127]
	v_mfma_f32_16x16x32_bf16 v[120:123], v[170:173], v[196:199], v[120:123]
	v_mfma_f32_16x16x32_bf16 v[108:111], v[162:165], v[204:207], v[108:111]
	v_mfma_f32_16x16x32_bf16 v[104:107], v[170:173], v[204:207], v[104:107]
	v_mfma_f32_16x16x32_bf16 v[92:95], v[162:165], v[212:215], v[92:95]
	v_mfma_f32_16x16x32_bf16 v[88:91], v[170:173], v[212:215], v[88:91]
	v_mfma_f32_16x16x32_bf16 v[76:79], v[162:165], v[220:223], v[76:79]
	v_mfma_f32_16x16x32_bf16 v[72:75], v[170:173], v[220:223], v[72:75]
	s_setprio 0
	s_setprio 1
	v_mfma_f32_16x16x32_bf16 v[116:119], v[174:177], v[192:195], v[116:119]
	v_mfma_f32_16x16x32_bf16 v[112:115], v[184:187], v[192:195], v[112:115]
	v_mfma_f32_16x16x32_bf16 v[100:103], v[174:177], v[200:203], v[100:103]
	v_mfma_f32_16x16x32_bf16 v[96:99], v[184:187], v[200:203], v[96:99]
	v_mfma_f32_16x16x32_bf16 v[84:87], v[174:177], v[208:211], v[84:87]
	v_mfma_f32_16x16x32_bf16 v[80:83], v[184:187], v[208:211], v[80:83]
	v_mfma_f32_16x16x32_bf16 v[68:71], v[174:177], v[216:219], v[68:71]
	v_mfma_f32_16x16x32_bf16 v[64:67], v[184:187], v[216:219], v[64:67]
	v_mfma_f32_16x16x32_bf16 v[116:119], v[178:181], v[196:199], v[116:119]
	v_mfma_f32_16x16x32_bf16 v[112:115], v[188:191], v[196:199], v[112:115]
	v_mfma_f32_16x16x32_bf16 v[100:103], v[178:181], v[204:207], v[100:103]
	v_mfma_f32_16x16x32_bf16 v[96:99], v[188:191], v[204:207], v[96:99]
	v_mfma_f32_16x16x32_bf16 v[84:87], v[178:181], v[212:215], v[84:87]
	v_mfma_f32_16x16x32_bf16 v[80:83], v[188:191], v[212:215], v[80:83]
	v_mfma_f32_16x16x32_bf16 v[68:71], v[178:181], v[220:223], v[68:71]
	v_mfma_f32_16x16x32_bf16 v[64:67], v[188:191], v[220:223], v[64:67]
	v_mfma_f32_16x16x32_bf16 v[246:249], v[240:243], v[208:211], v[246:249]
	v_mfma_f32_16x16x32_bf16 v[246:249], v[148:151], v[212:215], v[246:249]
	s_setprio 0
	s_barrier
	s_add_i32 s36, s56, s39
	v_lshl_add_u64 v[152:153], v[152:153], 0, s[12:13]
	s_mov_b32 m0, s36
	ds_read_b128 v[192:195], v156 offset:49152
	ds_read_b128 v[196:199], v156 offset:50176
	ds_read_b128 v[200:203], v156 offset:51200
	ds_read_b128 v[204:207], v156 offset:52224
	ds_read_b128 v[208:211], v156 offset:53248
	ds_read_b128 v[212:215], v156 offset:54272
	ds_read_b128 v[216:219], v156 offset:55296
	ds_read_b128 v[220:223], v156 offset:56320
	global_load_lds_dwordx4 v[152:153], off
	s_add_i32 m0, s36, 0x2000
	s_add_u32 s34, s34, 0x40080
	v_lshl_add_u64 v[152:153], v[224:225], 0, s[12:13]
	s_addc_u32 s35, s35, 0
	s_add_i32 s36, s57, s39
	global_load_lds_dwordx4 v[152:153], off
	v_lshl_add_u64 v[152:153], s[34:35], 0, v[130:131]
	s_mov_b32 m0, s36
	s_nop 0
	global_load_lds_dwordx4 v[152:153], off
	v_lshl_add_u64 v[152:153], s[34:35], 0, v[134:135]
	s_add_i32 m0, s36, 0x2000
	s_nop 0
	global_load_lds_dwordx4 v[152:153], off
	v_lshl_add_u64 v[152:153], v[226:227], 0, s[12:13]
	s_mov_b32 m0, s45
	s_nop 0
	global_load_lds_dwordx4 v[152:153], off
	v_lshl_add_u64 v[152:153], v[228:229], 0, s[12:13]
	s_mov_b32 m0, s46
	s_nop 0
	global_load_lds_dwordx4 v[152:153], off
	s_waitcnt vmcnt(10)
	s_waitcnt lgkmcnt(0)
	s_barrier
	s_setprio 1
	s_waitcnt lgkmcnt(0)
	v_mfma_f32_16x16x32_bf16 v[60:63], v[158:161], v[192:195], v[60:63]
	v_mfma_f32_16x16x32_bf16 v[56:59], v[166:169], v[192:195], v[56:59]
	v_mfma_f32_16x16x32_bf16 v[44:47], v[158:161], v[200:203], v[44:47]
	v_mfma_f32_16x16x32_bf16 v[40:43], v[166:169], v[200:203], v[40:43]
	v_mfma_f32_16x16x32_bf16 v[28:31], v[158:161], v[208:211], v[28:31]
	v_mfma_f32_16x16x32_bf16 v[24:27], v[166:169], v[208:211], v[24:27]
	v_mfma_f32_16x16x32_bf16 v[12:15], v[158:161], v[216:219], v[12:15]
	v_mfma_f32_16x16x32_bf16 v[8:11], v[166:169], v[216:219], v[8:11]
	v_mfma_f32_16x16x32_bf16 v[60:63], v[162:165], v[196:199], v[60:63]
	v_mfma_f32_16x16x32_bf16 v[56:59], v[170:173], v[196:199], v[56:59]
	v_mfma_f32_16x16x32_bf16 v[44:47], v[162:165], v[204:207], v[44:47]
	v_mfma_f32_16x16x32_bf16 v[40:43], v[170:173], v[204:207], v[40:43]
	v_mfma_f32_16x16x32_bf16 v[28:31], v[162:165], v[212:215], v[28:31]
	v_mfma_f32_16x16x32_bf16 v[24:27], v[170:173], v[212:215], v[24:27]
	v_mfma_f32_16x16x32_bf16 v[12:15], v[162:165], v[220:223], v[12:15]
	v_mfma_f32_16x16x32_bf16 v[8:11], v[170:173], v[220:223], v[8:11]
	s_setprio 0
	s_setprio 1
	v_mfma_f32_16x16x32_bf16 v[52:55], v[174:177], v[192:195], v[52:55]
	v_mfma_f32_16x16x32_bf16 v[48:51], v[184:187], v[192:195], v[48:51]
	v_mfma_f32_16x16x32_bf16 v[36:39], v[174:177], v[200:203], v[36:39]
	v_mfma_f32_16x16x32_bf16 v[32:35], v[184:187], v[200:203], v[32:35]
	v_mfma_f32_16x16x32_bf16 v[20:23], v[174:177], v[208:211], v[20:23]
	v_mfma_f32_16x16x32_bf16 v[16:19], v[184:187], v[208:211], v[16:19]
	v_mfma_f32_16x16x32_bf16 v[4:7], v[174:177], v[216:219], v[4:7]
	v_mfma_f32_16x16x32_bf16 v[0:3], v[184:187], v[216:219], v[0:3]
	v_mfma_f32_16x16x32_bf16 v[52:55], v[178:181], v[196:199], v[52:55]
	v_mfma_f32_16x16x32_bf16 v[48:51], v[188:191], v[196:199], v[48:51]
	v_mfma_f32_16x16x32_bf16 v[36:39], v[178:181], v[204:207], v[36:39]
	v_mfma_f32_16x16x32_bf16 v[32:35], v[188:191], v[204:207], v[32:35]
	v_mfma_f32_16x16x32_bf16 v[20:23], v[178:181], v[212:215], v[20:23]
	v_mfma_f32_16x16x32_bf16 v[16:19], v[188:191], v[212:215], v[16:19]
	v_mfma_f32_16x16x32_bf16 v[4:7], v[178:181], v[220:223], v[4:7]
	v_mfma_f32_16x16x32_bf16 v[0:3], v[188:191], v[220:223], v[0:3]
	v_mfma_f32_16x16x32_bf16 v[250:253], v[240:243], v[208:211], v[250:253]
	v_mfma_f32_16x16x32_bf16 v[250:253], v[148:151], v[212:215], v[250:253]
	s_setprio 0
	s_barrier
	s_add_i32 s55, s55, 2
	s_add_u32 s30, s30, 0x100
	s_addc_u32 s31, s31, 0
	s_add_u32 s53, s53, 0x100
	s_addc_u32 s54, s54, 0
	s_cmp_gt_u32 s55, 13
	s_cbranch_scc0 .Ldtf_loop2
	s_branch .Ldtf_exit
.Ldtf_loop3:
	ds_read_b128 v[158:161], v154
	ds_read_b128 v[162:165], v154 offset:1024
	ds_read_b128 v[166:169], v154 offset:2048
	ds_read_b128 v[170:173], v154 offset:3072
	ds_read_b128 v[174:177], v155
	ds_read_b128 v[178:181], v155 offset:1024
	ds_read_b128 v[184:187], v155 offset:2048
	ds_read_b128 v[188:191], v155 offset:3072
	s_add_u32 s34, s30, 0xfffc0080
	s_addc_u32 s35, s31, -1
	s_cmp_eq_u32 s55, 12
	s_cselect_b32 s37, s5, s35
	s_cselect_b32 s36, s8, s34
	s_cselect_b32 s35, s19, s54
	s_cselect_b32 s34, s25, s53
	v_lshl_add_u64 v[152:153], s[30:31], 0, v[142:143]
	s_add_i32 m0, s7, 0xc000
	ds_read_b128 v[192:195], v156
	ds_read_b128 v[196:199], v156 offset:1024
	ds_read_b128 v[200:203], v156 offset:2048
	ds_read_b128 v[204:207], v156 offset:3072
	ds_read_b128 v[208:211], v156 offset:4096
	ds_read_b128 v[212:215], v156 offset:5120
	ds_read_b128 v[216:219], v156 offset:6144
	ds_read_b128 v[220:223], v156 offset:7168
	global_load_lds_dwordx4 v[152:153], off
	v_lshl_add_u64 v[152:153], s[30:31], 0, v[146:147]
	s_add_i32 m0, s7, 0xe000
	s_nop 0
	global_load_lds_dwordx4 v[152:153], off
	global_load_dwordx4 v[240:243], v245, s[98:99]
	global_load_dwordx4 v[148:151], v245, s[98:99] offset:64
	s_add_u32 s98, s98, 0x80
	s_addc_u32 s99, s99, 0
	s_waitcnt vmcnt(10)
	s_waitcnt lgkmcnt(0)
	s_barrier
	s_setprio 1
	s_waitcnt lgkmcnt(0)
	v_mfma_f32_16x16x32_bf16 v[124:127], v[158:161], v[192:195], v[124:127]
	v_mfma_f32_16x16x32_bf16 v[120:123], v[166:169], v[192:195], v[120:123]
	v_mfma_f32_16x16x32_bf16 v[108:111], v[158:161], v[200:203], v[108:111]
	v_mfma_f32_16x16x32_bf16 v[104:107], v[166:169], v[200:203], v[104:107]
	v_mfma_f32_16x16x32_bf16 v[92:95], v[158:161], v[208:211], v[92:95]
	v_mfma_f32_16x16x32_bf16 v[88:91], v[166:169], v[208:211], v[88:91]
	v_mfma_f32_16x16x32_bf16 v[76:79], v[158:161], v[216:219], v[76:79]
	v_mfma_f32_16x16x32_bf16 v[72:75], v[166:169], v[216:219], v[72:75]
	v_mfma_f32_16x16x32_bf16 v[124:127], v[162:165], v[196:199], v[124:127]
	v_mfma_f32_16x16x32_bf16 v[120:123], v[170:173], v[196:199], v[120:123]
	v_mfma_f32_16x16x32_bf16 v[108:111], v[162:165], v[204:207], v[108:111]
	v_mfma_f32_16x16x32_bf16 v[104:107], v[170:173], v[204:207], v[104:107]
	v_mfma_f32_16x16x32_bf16 v[92:95], v[162:165], v[212:215], v[92:95]
	v_mfma_f32_16x16x32_bf16 v[88:91], v[170:173], v[212:215], v[88:91]
	v_mfma_f32_16x16x32_bf16 v[76:79], v[162:165], v[220:223], v[76:79]
	v_mfma_f32_16x16x32_bf16 v[72:75], v[170:173], v[220:223], v[72:75]
	s_setprio 0
	s_setprio 1
	v_mfma_f32_16x16x32_bf16 v[116:119], v[174:177], v[192:195], v[116:119]
	v_mfma_f32_16x16x32_bf16 v[112:115], v[184:187], v[192:195], v[112:115]
	v_mfma_f32_16x16x32_bf16 v[100:103], v[174:177], v[200:203], v[100:103]
	v_mfma_f32_16x16x32_bf16 v[96:99], v[184:187], v[200:203], v[96:99]
	v_mfma_f32_16x16x32_bf16 v[84:87], v[174:177], v[208:211], v[84:87]
	v_mfma_f32_16x16x32_bf16 v[80:83], v[184:187], v[208:211], v[80:83]
	v_mfma_f32_16x16x32_bf16 v[68:71], v[174:177], v[216:219], v[68:71]
	v_mfma_f32_16x16x32_bf16 v[64:67], v[184:187], v[216:219], v[64:67]
	v_mfma_f32_16x16x32_bf16 v[116:119], v[178:181], v[196:199], v[116:119]
	v_mfma_f32_16x16x32_bf16 v[112:115], v[188:191], v[196:199], v[112:115]
	v_mfma_f32_16x16x32_bf16 v[100:103], v[178:181], v[204:207], v[100:103]
	v_mfma_f32_16x16x32_bf16 v[96:99], v[188:191], v[204:207], v[96:99]
	v_mfma_f32_16x16x32_bf16 v[84:87], v[178:181], v[212:215], v[84:87]
	v_mfma_f32_16x16x32_bf16 v[80:83], v[188:191], v[212:215], v[80:83]
	v_mfma_f32_16x16x32_bf16 v[68:71], v[178:181], v[220:223], v[68:71]
	v_mfma_f32_16x16x32_bf16 v[64:67], v[188:191], v[220:223], v[64:67]
	v_mfma_f32_16x16x32_bf16 v[246:249], v[232:235], v[216:219], v[246:249]
	v_mfma_f32_16x16x32_bf16 v[246:249], v[236:239], v[220:223], v[246:249]
	s_setprio 0
	s_barrier
	s_add_i32 s56, s50, s39
	v_lshl_add_u64 v[152:153], s[34:35], 0, v[130:131]
	s_mov_b32 m0, s56
	ds_read_b128 v[192:195], v156 offset:16384
	ds_read_b128 v[196:199], v156 offset:17408
	ds_read_b128 v[200:203], v156 offset:18432
	ds_read_b128 v[204:207], v156 offset:19456
	ds_read_b128 v[208:211], v156 offset:20480
	ds_read_b128 v[212:215], v156 offset:21504
	ds_read_b128 v[216:219], v156 offset:22528
	ds_read_b128 v[220:223], v156 offset:23552
	global_load_lds_dwordx4 v[152:153], off
	s_add_i32 m0, s56, 0x2000
	s_add_u32 s56, s34, 0x40000
	v_lshl_add_u64 v[224:225], s[34:35], 0, v[134:135]
	s_addc_u32 s57, s35, 0
	s_add_i32 s58, s51, s39
	global_load_lds_dwordx4 v[224:225], off
	v_lshl_add_u64 v[226:227], s[56:57], 0, v[130:131]
	s_mov_b32 m0, s58
	v_lshl_add_u64 v[228:229], s[36:37], 0, v[132:133]
	global_load_lds_dwordx4 v[226:227], off
	v_lshl_add_u64 v[226:227], s[56:57], 0, v[134:135]
	s_add_i32 m0, s58, 0x2000
	s_nop 0
	global_load_lds_dwordx4 v[226:227], off
	v_lshl_add_u64 v[226:227], s[36:37], 0, v[128:129]
	s_mov_b32 m0, s7
	s_nop 0
	global_load_lds_dwordx4 v[226:227], off
	s_mov_b32 m0, s40
	s_nop 0
	global_load_lds_dwordx4 v[228:229], off
	s_waitcnt vmcnt(10)
	s_waitcnt lgkmcnt(0)
	s_barrier
	s_setprio 1
	s_waitcnt lgkmcnt(0)
	v_mfma_f32_16x16x32_bf16 v[60:63], v[158:161], v[192:195], v[60:63]
	v_mfma_f32_16x16x32_bf16 v[56:59], v[166:169], v[192:195], v[56:59]
	v_mfma_f32_16x16x32_bf16 v[44:47], v[158:161], v[200:203], v[44:47]
	v_mfma_f32_16x16x32_bf16 v[40:43], v[166:169], v[200:203], v[40:43]
	v_mfma_f32_16x16x32_bf16 v[28:31], v[158:161], v[208:211], v[28:31]
	v_mfma_f32_16x16x32_bf16 v[24:27], v[166:169], v[208:211], v[24:27]
	v_mfma_f32_16x16x32_bf16 v[12:15], v[158:161], v[216:219], v[12:15]
	v_mfma_f32_16x16x32_bf16 v[8:11], v[166:169], v[216:219], v[8:11]
	v_mfma_f32_16x16x32_bf16 v[60:63], v[162:165], v[196:199], v[60:63]
	v_mfma_f32_16x16x32_bf16 v[56:59], v[170:173], v[196:199], v[56:59]
	v_mfma_f32_16x16x32_bf16 v[44:47], v[162:165], v[204:207], v[44:47]
	v_mfma_f32_16x16x32_bf16 v[40:43], v[170:173], v[204:207], v[40:43]
	v_mfma_f32_16x16x32_bf16 v[28:31], v[162:165], v[212:215], v[28:31]
	v_mfma_f32_16x16x32_bf16 v[24:27], v[170:173], v[212:215], v[24:27]
	v_mfma_f32_16x16x32_bf16 v[12:15], v[162:165], v[220:223], v[12:15]
	v_mfma_f32_16x16x32_bf16 v[8:11], v[170:173], v[220:223], v[8:11]
	s_setprio 0
	s_setprio 1
	v_mfma_f32_16x16x32_bf16 v[52:55], v[174:177], v[192:195], v[52:55]
	v_mfma_f32_16x16x32_bf16 v[48:51], v[184:187], v[192:195], v[48:51]
	v_mfma_f32_16x16x32_bf16 v[36:39], v[174:177], v[200:203], v[36:39]
	v_mfma_f32_16x16x32_bf16 v[32:35], v[184:187], v[200:203], v[32:35]
	v_mfma_f32_16x16x32_bf16 v[20:23], v[174:177], v[208:211], v[20:23]
	v_mfma_f32_16x16x32_bf16 v[16:19], v[184:187], v[208:211], v[16:19]
	v_mfma_f32_16x16x32_bf16 v[4:7], v[174:177], v[216:219], v[4:7]
	v_mfma_f32_16x16x32_bf16 v[0:3], v[184:187], v[216:219], v[0:3]
	v_mfma_f32_16x16x32_bf16 v[52:55], v[178:181], v[196:199], v[52:55]
	v_mfma_f32_16x16x32_bf16 v[48:51], v[188:191], v[196:199], v[48:51]
	v_mfma_f32_16x16x32_bf16 v[36:39], v[178:181], v[204:207], v[36:39]
	v_mfma_f32_16x16x32_bf16 v[32:35], v[188:191], v[204:207], v[32:35]
	v_mfma_f32_16x16x32_bf16 v[20:23], v[178:181], v[212:215], v[20:23]
	v_mfma_f32_16x16x32_bf16 v[16:19], v[188:191], v[212:215], v[16:19]
	v_mfma_f32_16x16x32_bf16 v[4:7], v[178:181], v[220:223], v[4:7]
	v_mfma_f32_16x16x32_bf16 v[0:3], v[188:191], v[220:223], v[0:3]
	v_mfma_f32_16x16x32_bf16 v[250:253], v[232:235], v[216:219], v[250:253]
	v_mfma_f32_16x16x32_bf16 v[250:253], v[236:239], v[220:223], v[250:253]
	s_setprio 0
	s_barrier
	s_add_i32 s56, 0, 0x18000
	v_add_u32_e32 v136, s56, v145
	s_add_i32 s57, 0, 0x1c000
	ds_read_b128 v[158:161], v136
	ds_read_b128 v[162:165], v136 offset:1024
	ds_read_b128 v[166:169], v136 offset:2048
	ds_read_b128 v[170:173], v136 offset:3072
	v_add_u32_e32 v136, s57, v145
	ds_read_b128 v[174:177], v136
	ds_read_b128 v[178:181], v136 offset:1024
	ds_read_b128 v[184:187], v136 offset:2048
	ds_read_b128 v[188:191], v136 offset:3072
	s_add_u32 s36, s36, 0x40000
	s_addc_u32 s37, s37, 0
	s_mov_b32 m0, s41
	v_lshl_add_u64 v[230:231], s[36:37], 0, v[128:129]
	ds_read_b128 v[192:195], v156 offset:32768
	ds_read_b128 v[196:199], v156 offset:33792
	ds_read_b128 v[200:203], v156 offset:34816
	ds_read_b128 v[204:207], v156 offset:35840
	ds_read_b128 v[208:211], v156 offset:36864
	ds_read_b128 v[212:215], v156 offset:37888
	ds_read_b128 v[216:219], v156 offset:38912
	ds_read_b128 v[220:223], v156 offset:39936
	global_load_lds_dwordx4 v[230:231], off
	v_lshl_add_u64 v[230:231], s[36:37], 0, v[132:133]
	s_mov_b32 m0, s42
	s_nop 0
	global_load_lds_dwordx4 v[230:231], off
	global_load_dwordx4 v[232:235], v245, s[98:99]
	global_load_dwordx4 v[236:239], v245, s[98:99] offset:64
	s_add_u32 s98, s98, 0x80
	s_addc_u32 s99, s99, 0
	s_waitcnt vmcnt(10)
	s_waitcnt lgkmcnt(0)
	s_barrier
	s_setprio 1
	s_waitcnt lgkmcnt(0)
	v_mfma_f32_16x16x32_bf16 v[124:127], v[158:161], v[192:195], v[124:127]
	v_mfma_f32_16x16x32_bf16 v[120:123], v[166:169], v[192:195], v[120:123]
	v_mfma_f32_16x16x32_bf16 v[108:111], v[158:161], v[200:203], v[108:111]
	v_mfma_f32_16x16x32_bf16 v[104:107], v[166:169], v[200:203], v[104:107]
	v_mfma_f32_16x16x32_bf16 v[92:95], v[158:161], v[208:211], v[92:95]
	v_mfma_f32_16x16x32_bf16 v[88:91], v[166:169], v[208:211], v[88:91]
	v_mfma_f32_16x16x32_bf16 v[76:79], v[158:161], v[216:219], v[76:79]
	v_mfma_f32_16x16x32_bf16 v[72:75], v[166:169], v[216:219], v[72:75]
	v_mfma_f32_16x16x32_bf16 v[124:127], v[162:165], v[196:199], v[124:127]
	v_mfma_f32_16x16x32_bf16 v[120:123], v[170:173], v[196:199], v[120:123]
	v_mfma_f32_16x16x32_bf16 v[108:111], v[162:165], v[204:207], v[108:111]
	v_mfma_f32_16x16x32_bf16 v[104:107], v[170:173], v[204:207], v[104:107]
	v_mfma_f32_16x16x32_bf16 v[92:95], v[162:165], v[212:215], v[92:95]
	v_mfma_f32_16x16x32_bf16 v[88:91], v[170:173], v[212:215], v[88:91]
	v_mfma_f32_16x16x32_bf16 v[76:79], v[162:165], v[220:223], v[76:79]
	v_mfma_f32_16x16x32_bf16 v[72:75], v[170:173], v[220:223], v[72:75]
	s_setprio 0
	s_setprio 1
	v_mfma_f32_16x16x32_bf16 v[116:119], v[174:177], v[192:195], v[116:119]
	v_mfma_f32_16x16x32_bf16 v[112:115], v[184:187], v[192:195], v[112:115]
	v_mfma_f32_16x16x32_bf16 v[100:103], v[174:177], v[200:203], v[100:103]
	v_mfma_f32_16x16x32_bf16 v[96:99], v[184:187], v[200:203], v[96:99]
	v_mfma_f32_16x16x32_bf16 v[84:87], v[174:177], v[208:211], v[84:87]
	v_mfma_f32_16x16x32_bf16 v[80:83], v[184:187], v[208:211], v[80:83]
	v_mfma_f32_16x16x32_bf16 v[68:71], v[174:177], v[216:219], v[68:71]
	v_mfma_f32_16x16x32_bf16 v[64:67], v[184:187], v[216:219], v[64:67]
	v_mfma_f32_16x16x32_bf16 v[116:119], v[178:181], v[196:199], v[116:119]
	v_mfma_f32_16x16x32_bf16 v[112:115], v[188:191], v[196:199], v[112:115]
	v_mfma_f32_16x16x32_bf16 v[100:103], v[178:181], v[204:207], v[100:103]
	v_mfma_f32_16x16x32_bf16 v[96:99], v[188:191], v[204:207], v[96:99]
	v_mfma_f32_16x16x32_bf16 v[84:87], v[178:181], v[212:215], v[84:87]
	v_mfma_f32_16x16x32_bf16 v[80:83], v[188:191], v[212:215], v[80:83]
	v_mfma_f32_16x16x32_bf16 v[68:71], v[178:181], v[220:223], v[68:71]
	v_mfma_f32_16x16x32_bf16 v[64:67], v[188:191], v[220:223], v[64:67]
	v_mfma_f32_16x16x32_bf16 v[246:249], v[240:243], v[216:219], v[246:249]
	v_mfma_f32_16x16x32_bf16 v[246:249], v[148:151], v[220:223], v[246:249]
	s_setprio 0
	s_barrier
	s_add_i32 s36, s56, s39
	v_lshl_add_u64 v[152:153], v[152:153], 0, s[12:13]
	s_mov_b32 m0, s36
	ds_read_b128 v[192:195], v156 offset:49152
	ds_read_b128 v[196:199], v156 offset:50176
	ds_read_b128 v[200:203], v156 offset:51200
	ds_read_b128 v[204:207], v156 offset:52224
	ds_read_b128 v[208:211], v156 offset:53248
	ds_read_b128 v[212:215], v156 offset:54272
	ds_read_b128 v[216:219], v156 offset:55296
	ds_read_b128 v[220:223], v156 offset:56320
	global_load_lds_dwordx4 v[152:153], off
	s_add_i32 m0, s36, 0x2000
	s_add_u32 s34, s34, 0x40080
	v_lshl_add_u64 v[152:153], v[224:225], 0, s[12:13]
	s_addc_u32 s35, s35, 0
	s_add_i32 s36, s57, s39
	global_load_lds_dwordx4 v[152:153], off
	v_lshl_add_u64 v[152:153], s[34:35], 0, v[130:131]
	s_mov_b32 m0, s36
	s_nop 0
	global_load_lds_dwordx4 v[152:153], off
	v_lshl_add_u64 v[152:153], s[34:35], 0, v[134:135]
	s_add_i32 m0, s36, 0x2000
	s_nop 0
	global_load_lds_dwordx4 v[152:153], off
	v_lshl_add_u64 v[152:153], v[226:227], 0, s[12:13]
	s_mov_b32 m0, s45
	s_nop 0
	global_load_lds_dwordx4 v[152:153], off
	v_lshl_add_u64 v[152:153], v[228:229], 0, s[12:13]
	s_mov_b32 m0, s46
	s_nop 0
	global_load_lds_dwordx4 v[152:153], off
	s_waitcnt vmcnt(10)
	s_waitcnt lgkmcnt(0)
	s_barrier
	s_setprio 1
	s_waitcnt lgkmcnt(0)
	v_mfma_f32_16x16x32_bf16 v[60:63], v[158:161], v[192:195], v[60:63]
	v_mfma_f32_16x16x32_bf16 v[56:59], v[166:169], v[192:195], v[56:59]
	v_mfma_f32_16x16x32_bf16 v[44:47], v[158:161], v[200:203], v[44:47]
	v_mfma_f32_16x16x32_bf16 v[40:43], v[166:169], v[200:203], v[40:43]
	v_mfma_f32_16x16x32_bf16 v[28:31], v[158:161], v[208:211], v[28:31]
	v_mfma_f32_16x16x32_bf16 v[24:27], v[166:169], v[208:211], v[24:27]
	v_mfma_f32_16x16x32_bf16 v[12:15], v[158:161], v[216:219], v[12:15]
	v_mfma_f32_16x16x32_bf16 v[8:11], v[166:169], v[216:219], v[8:11]
	v_mfma_f32_16x16x32_bf16 v[60:63], v[162:165], v[196:199], v[60:63]
	v_mfma_f32_16x16x32_bf16 v[56:59], v[170:173], v[196:199], v[56:59]
	v_mfma_f32_16x16x32_bf16 v[44:47], v[162:165], v[204:207], v[44:47]
	v_mfma_f32_16x16x32_bf16 v[40:43], v[170:173], v[204:207], v[40:43]
	v_mfma_f32_16x16x32_bf16 v[28:31], v[162:165], v[212:215], v[28:31]
	v_mfma_f32_16x16x32_bf16 v[24:27], v[170:173], v[212:215], v[24:27]
	v_mfma_f32_16x16x32_bf16 v[12:15], v[162:165], v[220:223], v[12:15]
	v_mfma_f32_16x16x32_bf16 v[8:11], v[170:173], v[220:223], v[8:11]
	s_setprio 0
	s_setprio 1
	v_mfma_f32_16x16x32_bf16 v[52:55], v[174:177], v[192:195], v[52:55]
	v_mfma_f32_16x16x32_bf16 v[48:51], v[184:187], v[192:195], v[48:51]
	v_mfma_f32_16x16x32_bf16 v[36:39], v[174:177], v[200:203], v[36:39]
	v_mfma_f32_16x16x32_bf16 v[32:35], v[184:187], v[200:203], v[32:35]
	v_mfma_f32_16x16x32_bf16 v[20:23], v[174:177], v[208:211], v[20:23]
	v_mfma_f32_16x16x32_bf16 v[16:19], v[184:187], v[208:211], v[16:19]
	v_mfma_f32_16x16x32_bf16 v[4:7], v[174:177], v[216:219], v[4:7]
	v_mfma_f32_16x16x32_bf16 v[0:3], v[184:187], v[216:219], v[0:3]
	v_mfma_f32_16x16x32_bf16 v[52:55], v[178:181], v[196:199], v[52:55]
	v_mfma_f32_16x16x32_bf16 v[48:51], v[188:191], v[196:199], v[48:51]
	v_mfma_f32_16x16x32_bf16 v[36:39], v[178:181], v[204:207], v[36:39]
	v_mfma_f32_16x16x32_bf16 v[32:35], v[188:191], v[204:207], v[32:35]
	v_mfma_f32_16x16x32_bf16 v[20:23], v[178:181], v[212:215], v[20:23]
	v_mfma_f32_16x16x32_bf16 v[16:19], v[188:191], v[212:215], v[16:19]
	v_mfma_f32_16x16x32_bf16 v[4:7], v[178:181], v[220:223], v[4:7]
	v_mfma_f32_16x16x32_bf16 v[0:3], v[188:191], v[220:223], v[0:3]
	v_mfma_f32_16x16x32_bf16 v[250:253], v[240:243], v[216:219], v[250:253]
	v_mfma_f32_16x16x32_bf16 v[250:253], v[148:151], v[220:223], v[250:253]
	s_setprio 0
	s_barrier
	s_add_i32 s55, s55, 2
	s_add_u32 s30, s30, 0x100
	s_addc_u32 s31, s31, 0
	s_add_u32 s53, s53, 0x100
	s_addc_u32 s54, s54, 0
	s_cmp_gt_u32 s55, 13
	s_cbranch_scc0 .Ldtf_loop3
